# combo30: combo28 + pass C issues all four q/Btab load groups together (12 loads, renamed registers, counted waits) instead of four load-wait-compute rounds
# baseline (speedup 1.0000x reference)
; __device__ __forceinline__ unsigned pk2(float lo, float hi) { const f32x2 v = {lo, hi}; return __builtin_bit_cast(unsigned, __builtin_convertvector(v, hwbf16x2)); }
; __device__ __forceinline__ void gla_pass_c(LAS unsigned char* ldsl, const bf16_t* __restrict__ proj, const float* __restrict__ Btab, const float* __restrict__ Gst, const float* __restrict__ gout, bf16_t* __restrict__ mixed) {
;     ...
;         { const bf16_t* qp = proj + (row0 + tl) * NIN + h * 64; const float* bp = Btab + (row0 + tl) * 256 + h * 64;
; #pragma unroll
;           for (int ks = 0; ks < 4; ++ks) { const u32x4 qw = *(const u32x4*)(qp + 16 * ks + 8 * hh); const f32x4 b0 = *(const f32x4*)(bp + 16 * ks + 8 * hh), b1 = *(const f32x4*)(bp + 16 * ks + 8 * hh + 4);
;               u32x4 w; w.x = pk2(__uint_as_float(qw[0] << 16) * 0.125f * __expf(b0[0]), __uint_as_float(qw[0] & 0xffff0000u) * 0.125f * __expf(b0[1]));
;                        w.y = pk2(__uint_as_float(qw[1] << 16) * 0.125f * __expf(b0[2]), __uint_as_float(qw[1] & 0xffff0000u) * 0.125f * __expf(b0[3]));
;                        w.z = pk2(__uint_as_float(qw[2] << 16) * 0.125f * __expf(b1[0]), __uint_as_float(qw[2] & 0xffff0000u) * 0.125f * __expf(b1[1]));
;                        w.w = pk2(__uint_as_float(qw[3] << 16) * 0.125f * __expf(b1[2]), __uint_as_float(qw[3] & 0xffff0000u) * 0.125f * __expf(b1[3]));
;               qe[ks] = __builtin_bit_cast(bf16x8, w); } }
.LBB0_876:
	v_lshrrev_b32_e32 v2, 8, v111
	s_lshl_b32 s2, s3, 5
	v_and_b32_e32 v70, 3, v2
	v_or3_b32 v2, s2, v108, v122
	v_mov_b32_e32 v3, v123
	v_lshlrev_b64 v[4:5], 12, v[2:3]
	v_lshlrev_b64 v[2:3], 10, v[2:3]
	v_lshlrev_b32_e32 v124, 7, v1
	v_mov_b32_e32 v125, v161
	v_lshl_add_u64 v[4:5], s[60:61], 0, v[4:5]
	v_lshl_add_u64 v[2:3], s[58:59], 0, v[2:3]
	v_lshl_add_u64 v[4:5], v[4:5], 0, v[124:125]
	v_lshl_add_u64 v[6:7], v[2:3], 0, v[160:161]
	v_lshlrev_b32_e32 v160, 1, v112
	v_lshl_add_u64 v[2:3], v[4:5], 0, v[160:161]
	v_lshlrev_b32_e32 v160, 2, v112
	v_lshl_add_u64 v[4:5], v[6:7], 0, v[160:161]
	global_load_dwordx4 v[6:9], v[2:3], off
	global_load_dwordx4 v[10:13], v[4:5], off offset:16
	global_load_dwordx4 v[14:17], v[4:5], off
	global_load_dwordx4 v[148:151], v[2:3], off offset:32
	global_load_dwordx4 v[152:155], v[4:5], off offset:80
	global_load_dwordx4 v[156:159], v[4:5], off offset:64
	global_load_dwordx4 v[162:165], v[2:3], off offset:64
	global_load_dwordx4 v[166:169], v[4:5], off offset:144
	global_load_dwordx4 v[170:173], v[4:5], off offset:128
	global_load_dwordx4 v[174:177], v[2:3], off offset:96
	global_load_dwordx4 v[178:181], v[4:5], off offset:208
	global_load_dwordx4 v[182:185], v[4:5], off offset:192
	s_mov_b32 s42, 0x3e000000
	s_movk_i32 s33, 0x2000
	v_mov_b32_e32 v67, v161
	v_lshl_add_u64 v[64:65], v[108:109], 0, v[64:65]
	v_lshl_add_u64 v[64:65], v[64:65], 0, v[66:67]
	v_lshlrev_b64 v[66:67], 12, v[64:65]
	v_lshlrev_b64 v[64:65], 10, v[64:65]
	v_lshl_or_b32 v66, v70, 7, v66
	v_lshl_or_b32 v64, v70, 8, v64
	s_sub_i32 s3, 0, s3
	v_lshl_add_u64 v[126:127], v[116:117], 0, v[66:67]
	v_lshl_add_u64 v[128:129], v[118:119], 0, v[64:65]
	v_mov_b32_e32 v121, v139
	s_waitcnt vmcnt(11)
	v_lshlrev_b32_e32 v18, 16, v6
	v_and_b32_e32 v19, 0xffff0000, v6
	s_waitcnt vmcnt(9)
	v_mul_f32_e32 v1, 0x3fb8aa3b, v14
	v_exp_f32_e32 v14, v1
	v_mul_f32_e32 v1, 0x3fb8aa3b, v15
	v_exp_f32_e32 v15, v1
	v_pk_mul_f32 v[18:19], v[18:19], s[42:43] op_sel_hi:[1,0]
	v_mul_f32_e32 v1, 0x3fb8aa3b, v16
	v_lshlrev_b32_e32 v6, 16, v7
	v_pk_mul_f32 v[14:15], v[18:19], v[14:15]
	v_and_b32_e32 v7, 0xffff0000, v7
	v_cvt_pk_bf16_f32 v80, v14, v15
	v_exp_f32_e32 v14, v1
	v_mul_f32_e32 v1, 0x3fb8aa3b, v17
	v_exp_f32_e32 v15, v1
	v_pk_mul_f32 v[6:7], v[6:7], s[42:43] op_sel_hi:[1,0]
	v_mul_f32_e32 v1, 0x3fb8aa3b, v10
	v_lshlrev_b32_e32 v10, 16, v8
	v_pk_mul_f32 v[6:7], v[6:7], v[14:15]
	s_nop 0
	v_cvt_pk_bf16_f32 v81, v6, v7
	v_exp_f32_e32 v6, v1
	v_mul_f32_e32 v1, 0x3fb8aa3b, v11
	v_exp_f32_e32 v7, v1
	v_and_b32_e32 v11, 0xffff0000, v8
	v_pk_mul_f32 v[10:11], v[10:11], s[42:43] op_sel_hi:[1,0]
	v_mul_f32_e32 v1, 0x3fb8aa3b, v12
	v_pk_mul_f32 v[6:7], v[10:11], v[6:7]
	v_lshlrev_b32_e32 v8, 16, v9
	v_cvt_pk_bf16_f32 v82, v6, v7
	v_exp_f32_e32 v6, v1
	v_mul_f32_e32 v1, 0x3fb8aa3b, v13
	v_exp_f32_e32 v7, v1
	v_and_b32_e32 v9, 0xffff0000, v9
	v_pk_mul_f32 v[8:9], v[8:9], s[42:43] op_sel_hi:[1,0]
	s_nop 0
	v_pk_mul_f32 v[6:7], v[8:9], v[6:7]
	s_nop 0
	v_cvt_pk_bf16_f32 v83, v6, v7
	s_waitcnt vmcnt(8)
	v_lshlrev_b32_e32 v18, 16, v148
	v_and_b32_e32 v19, 0xffff0000, v148
	s_waitcnt vmcnt(6)
	v_mul_f32_e32 v1, 0x3fb8aa3b, v156
	v_exp_f32_e32 v14, v1
	v_mul_f32_e32 v1, 0x3fb8aa3b, v157
	v_exp_f32_e32 v15, v1
	v_pk_mul_f32 v[18:19], v[18:19], s[42:43] op_sel_hi:[1,0]
	v_mul_f32_e32 v1, 0x3fb8aa3b, v158
	v_lshlrev_b32_e32 v6, 16, v149
	v_pk_mul_f32 v[14:15], v[18:19], v[14:15]
	v_and_b32_e32 v7, 0xffff0000, v149
	v_cvt_pk_bf16_f32 v84, v14, v15
	v_exp_f32_e32 v14, v1
	v_mul_f32_e32 v1, 0x3fb8aa3b, v159
	v_exp_f32_e32 v15, v1
	v_pk_mul_f32 v[6:7], v[6:7], s[42:43] op_sel_hi:[1,0]
	v_mul_f32_e32 v1, 0x3fb8aa3b, v152
	v_lshlrev_b32_e32 v10, 16, v150
	v_pk_mul_f32 v[6:7], v[6:7], v[14:15]
	s_nop 0
	v_cvt_pk_bf16_f32 v85, v6, v7
	v_exp_f32_e32 v6, v1
	v_mul_f32_e32 v1, 0x3fb8aa3b, v153
	v_exp_f32_e32 v7, v1
	v_and_b32_e32 v11, 0xffff0000, v150
	v_pk_mul_f32 v[10:11], v[10:11], s[42:43] op_sel_hi:[1,0]
	v_mul_f32_e32 v1, 0x3fb8aa3b, v154
	v_pk_mul_f32 v[6:7], v[10:11], v[6:7]
	v_lshlrev_b32_e32 v8, 16, v151
	v_cvt_pk_bf16_f32 v86, v6, v7
	v_exp_f32_e32 v6, v1
	v_mul_f32_e32 v1, 0x3fb8aa3b, v155
	v_exp_f32_e32 v7, v1
	v_and_b32_e32 v9, 0xffff0000, v151
	v_pk_mul_f32 v[8:9], v[8:9], s[42:43] op_sel_hi:[1,0]
	s_nop 0
	v_pk_mul_f32 v[6:7], v[8:9], v[6:7]
	s_nop 0
	v_cvt_pk_bf16_f32 v87, v6, v7
	s_waitcnt vmcnt(5)
	v_lshlrev_b32_e32 v18, 16, v162
	v_and_b32_e32 v19, 0xffff0000, v162
	s_waitcnt vmcnt(3)
	v_mul_f32_e32 v1, 0x3fb8aa3b, v170
	v_exp_f32_e32 v14, v1
	v_mul_f32_e32 v1, 0x3fb8aa3b, v171
	v_exp_f32_e32 v15, v1
	v_pk_mul_f32 v[18:19], v[18:19], s[42:43] op_sel_hi:[1,0]
	v_mul_f32_e32 v1, 0x3fb8aa3b, v172
	v_lshlrev_b32_e32 v6, 16, v163
	v_pk_mul_f32 v[14:15], v[18:19], v[14:15]
	v_and_b32_e32 v7, 0xffff0000, v163
	v_cvt_pk_bf16_f32 v88, v14, v15
	v_exp_f32_e32 v14, v1
	v_mul_f32_e32 v1, 0x3fb8aa3b, v173
	v_exp_f32_e32 v15, v1
	v_pk_mul_f32 v[6:7], v[6:7], s[42:43] op_sel_hi:[1,0]
	v_mul_f32_e32 v1, 0x3fb8aa3b, v166
	v_lshlrev_b32_e32 v10, 16, v164
	v_pk_mul_f32 v[6:7], v[6:7], v[14:15]
	s_nop 0
	v_cvt_pk_bf16_f32 v89, v6, v7
	v_exp_f32_e32 v6, v1
	v_mul_f32_e32 v1, 0x3fb8aa3b, v167
	v_exp_f32_e32 v7, v1
	v_and_b32_e32 v11, 0xffff0000, v164
	v_pk_mul_f32 v[10:11], v[10:11], s[42:43] op_sel_hi:[1,0]
	v_mul_f32_e32 v1, 0x3fb8aa3b, v168
	v_pk_mul_f32 v[6:7], v[10:11], v[6:7]
	v_lshlrev_b32_e32 v8, 16, v165
	v_cvt_pk_bf16_f32 v90, v6, v7
	v_exp_f32_e32 v6, v1
	v_mul_f32_e32 v1, 0x3fb8aa3b, v169
	v_exp_f32_e32 v7, v1
	v_and_b32_e32 v9, 0xffff0000, v165
	v_pk_mul_f32 v[8:9], v[8:9], s[42:43] op_sel_hi:[1,0]
	s_nop 0
	v_pk_mul_f32 v[6:7], v[8:9], v[6:7]
	s_nop 0
	v_cvt_pk_bf16_f32 v91, v6, v7
	s_nop 0
	s_waitcnt vmcnt(2)
; __device__ __forceinline__ unsigned pk2(float lo, float hi) { const f32x2 v = {lo, hi}; return __builtin_bit_cast(unsigned, __builtin_convertvector(v, hwbf16x2)); }
; __device__ __forceinline__ void gla_pass_c(LAS unsigned char* ldsl, const bf16_t* __restrict__ proj, const float* __restrict__ Btab, const float* __restrict__ Gst, const float* __restrict__ gout, bf16_t* __restrict__ mixed) {
;     ...
;                        w.z = pk2(__uint_as_float(qw[2] << 16) * 0.125f * __expf(b1[0]), __uint_as_float(qw[2] & 0xffff0000u) * 0.125f * __expf(b1[1]));
;                        w.w = pk2(__uint_as_float(qw[3] << 16) * 0.125f * __expf(b1[2]), __uint_as_float(qw[3] & 0xffff0000u) * 0.125f * __expf(b1[3]));
;               qe[ks] = __builtin_bit_cast(bf16x8, w); } }
;         f32x16 o[4] = {};
; #pragma unroll
;         for (int dvb = 0; dvb < 4; ++dvb) { const float* sp = Gst + ((size_t)item * 128 + 32 * dvb + r) * 64;
; #pragma unroll
;           for (int ks = 0; ks < 4; ++ks) { const f32x4 s0 = *(const f32x4*)(sp + 16 * ks + 8 * hh), s1 = *(const f32x4*)(sp + 16 * ks + 8 * hh + 4);
;               u32x4 sw; sw.x = pk2(s0[0], s0[1]); sw.y = pk2(s0[2], s0[3]); sw.z = pk2(s1[0], s1[1]); sw.w = pk2(s1[2], s1[3]);
;               o[dvb] = __builtin_amdgcn_mfma_f32_32x32x16_bf16(qe[ks], __builtin_bit_cast(bf16x8, sw), o[dvb], 0, 0, 0); } }
	v_lshlrev_b32_e32 v14, 16, v174
	v_and_b32_e32 v15, 0xffff0000, v174
	s_waitcnt vmcnt(0)
	v_mul_f32_e32 v1, 0x3fb8aa3b, v182
	v_exp_f32_e32 v2, v1
	v_mul_f32_e32 v1, 0x3fb8aa3b, v183
	v_exp_f32_e32 v3, v1
	v_pk_mul_f32 v[14:15], v[14:15], s[42:43] op_sel_hi:[1,0]
	v_mul_f32_e32 v1, 0x3fb8aa3b, v184
	v_lshlrev_b32_e32 v4, 16, v175
	v_pk_mul_f32 v[2:3], v[14:15], v[2:3]
	s_nop 0
	v_cvt_pk_bf16_f32 v92, v2, v3
	v_exp_f32_e32 v2, v1
	v_mul_f32_e32 v1, 0x3fb8aa3b, v185
	v_exp_f32_e32 v3, v1
	v_and_b32_e32 v5, 0xffff0000, v175
	v_pk_mul_f32 v[4:5], v[4:5], s[42:43] op_sel_hi:[1,0]
	v_mul_f32_e32 v1, 0x3fb8aa3b, v178
	v_pk_mul_f32 v[2:3], v[4:5], v[2:3]
	v_lshlrev_b32_e32 v4, 16, v176
	v_cvt_pk_bf16_f32 v93, v2, v3
	v_exp_f32_e32 v2, v1
	v_mul_f32_e32 v1, 0x3fb8aa3b, v179
	v_exp_f32_e32 v3, v1
	v_and_b32_e32 v5, 0xffff0000, v176
	v_pk_mul_f32 v[4:5], v[4:5], s[42:43] op_sel_hi:[1,0]
	v_mul_f32_e32 v1, 0x3fb8aa3b, v180
	v_pk_mul_f32 v[2:3], v[4:5], v[2:3]
	v_lshlrev_b32_e32 v4, 16, v177
	v_cvt_pk_bf16_f32 v94, v2, v3
	v_exp_f32_e32 v2, v1
	v_mul_f32_e32 v1, 0x3fb8aa3b, v181
	v_exp_f32_e32 v3, v1
	v_and_b32_e32 v5, 0xffff0000, v177
	v_ashrrev_i32_e32 v1, 31, v0
	v_pk_mul_f32 v[4:5], v[4:5], s[42:43] op_sel_hi:[1,0]
	v_lshlrev_b64 v[0:1], 15, v[0:1]
	v_pk_mul_f32 v[2:3], v[4:5], v[2:3]
	v_lshl_add_u64 v[68:69], v[114:115], 0, v[0:1]
	v_cvt_pk_bf16_f32 v95, v2, v3
	global_load_dwordx4 v[0:3], v[68:69], off offset:16
	global_load_dwordx4 v[4:7], v[68:69], off
	global_load_dwordx4 v[16:19], v[68:69], off offset:80
	global_load_dwordx4 v[20:23], v[68:69], off offset:64
	v_add_co_u32_e32 v40, vcc, s33, v68
	s_mov_b64 s[42:43], 0x2040
	s_nop 0
	v_addc_co_u32_e32 v41, vcc, 0, v69, vcc
	v_lshl_add_u64 v[36:37], v[68:69], 0, s[42:43]
	s_mov_b64 s[42:43], 0x2080
	s_movk_i32 s33, 0x6000
	s_waitcnt vmcnt(2)
	v_cvt_pk_bf16_f32 v4, v4, v5
	v_cvt_pk_bf16_f32 v5, v6, v7
	v_cvt_pk_bf16_f32 v6, v0, v1
	v_cvt_pk_bf16_f32 v7, v2, v3
	s_waitcnt vmcnt(0)
	v_cvt_pk_bf16_f32 v20, v20, v21
	v_cvt_pk_bf16_f32 v21, v22, v23
	v_mfma_f32_32x32x16_bf16 v[0:15], v[80:83], v[4:7], 0
	v_cvt_pk_bf16_f32 v22, v16, v17
	v_cvt_pk_bf16_f32 v23, v18, v19
	s_nop 1
	v_mfma_f32_32x32x16_bf16 v[0:15], v[84:87], v[20:23], v[0:15]
	global_load_dwordx4 v[16:19], v[68:69], off offset:144
	global_load_dwordx4 v[20:23], v[68:69], off offset:128
	s_waitcnt vmcnt(0)
	v_cvt_pk_bf16_f32 v20, v20, v21
	v_cvt_pk_bf16_f32 v21, v22, v23
	v_cvt_pk_bf16_f32 v22, v16, v17
	v_cvt_pk_bf16_f32 v23, v18, v19
	s_nop 1
	v_mfma_f32_32x32x16_bf16 v[0:15], v[88:91], v[20:23], v[0:15]
	global_load_dwordx4 v[16:19], v[68:69], off offset:208
	global_load_dwordx4 v[20:23], v[68:69], off offset:192
	s_waitcnt vmcnt(0)
	v_cvt_pk_bf16_f32 v20, v20, v21
	v_cvt_pk_bf16_f32 v21, v22, v23
	v_cvt_pk_bf16_f32 v22, v16, v17
	v_cvt_pk_bf16_f32 v23, v18, v19
	v_lshl_add_u64 v[16:17], v[68:69], 0, s[44:45]
	s_nop 0
	v_mfma_f32_32x32x16_bf16 v[0:15], v[92:95], v[20:23], v[0:15]
	global_load_dwordx4 v[18:21], v[40:41], off
	global_load_dwordx4 v[22:25], v[16:17], off offset:16
	global_load_dwordx4 v[32:35], v[40:41], off offset:64
	s_nop 0
	global_load_dwordx4 v[36:39], v[36:37], off offset:16
	s_waitcnt vmcnt(3)
	v_cvt_pk_bf16_f32 v16, v18, v19
	v_cvt_pk_bf16_f32 v17, v20, v21
	s_waitcnt vmcnt(2)
	v_cvt_pk_bf16_f32 v18, v22, v23
	v_cvt_pk_bf16_f32 v19, v24, v25
	s_waitcnt vmcnt(1)
	v_cvt_pk_bf16_f32 v32, v32, v33
	v_cvt_pk_bf16_f32 v33, v34, v35
	v_mfma_f32_32x32x16_bf16 v[16:31], v[80:83], v[16:19], 0
	s_waitcnt vmcnt(0)
	v_cvt_pk_bf16_f32 v34, v36, v37
	v_cvt_pk_bf16_f32 v35, v38, v39
	v_lshl_add_u64 v[36:37], v[68:69], 0, s[42:43]
	s_mov_b64 s[42:43], 0x20c0
	v_mfma_f32_32x32x16_bf16 v[16:31], v[84:87], v[32:35], v[16:31]
	global_load_dwordx4 v[32:35], v[40:41], off offset:128
	s_nop 0
	global_load_dwordx4 v[36:39], v[36:37], off offset:16
	s_waitcnt vmcnt(1)
	v_cvt_pk_bf16_f32 v32, v32, v33
	v_cvt_pk_bf16_f32 v33, v34, v35
	s_waitcnt vmcnt(0)
; __device__ __forceinline__ unsigned pk2(float lo, float hi) { const f32x2 v = {lo, hi}; return __builtin_bit_cast(unsigned, __builtin_convertvector(v, hwbf16x2)); }
; __device__ __forceinline__ void gla_pass_c(LAS unsigned char* ldsl, const bf16_t* __restrict__ proj, const float* __restrict__ Btab, const float* __restrict__ Gst, const float* __restrict__ gout, bf16_t* __restrict__ mixed) {
;     ...
;         for (int dvb = 0; dvb < 4; ++dvb) { const float* sp = Gst + ((size_t)item * 128 + 32 * dvb + r) * 64;
; #pragma unroll
;           for (int ks = 0; ks < 4; ++ks) { const f32x4 s0 = *(const f32x4*)(sp + 16 * ks + 8 * hh), s1 = *(const f32x4*)(sp + 16 * ks + 8 * hh + 4);
;               u32x4 sw; sw.x = pk2(s0[0], s0[1]); sw.y = pk2(s0[2], s0[3]); sw.z = pk2(s1[0], s1[1]); sw.w = pk2(s1[2], s1[3]);
;               o[dvb] = __builtin_amdgcn_mfma_f32_32x32x16_bf16(qe[ks], __builtin_bit_cast(bf16x8, sw), o[dvb], 0, 0, 0); } }
	v_cvt_pk_bf16_f32 v34, v36, v37
	v_cvt_pk_bf16_f32 v35, v38, v39
	v_lshl_add_u64 v[36:37], v[68:69], 0, s[42:43]
	s_mov_b64 s[42:43], 0x4000
	v_mfma_f32_32x32x16_bf16 v[16:31], v[88:91], v[32:35], v[16:31]
	global_load_dwordx4 v[32:35], v[40:41], off offset:192
	s_nop 0
	global_load_dwordx4 v[36:39], v[36:37], off offset:16
	v_add_co_u32_e32 v40, vcc, s49, v68
	s_waitcnt vmcnt(1)
	v_cvt_pk_bf16_f32 v32, v32, v33
	v_cvt_pk_bf16_f32 v33, v34, v35
	s_waitcnt vmcnt(0)
	v_cvt_pk_bf16_f32 v34, v36, v37
	v_cvt_pk_bf16_f32 v35, v38, v39
	v_lshl_add_u64 v[36:37], v[68:69], 0, s[42:43]
	v_addc_co_u32_e32 v41, vcc, 0, v69, vcc
	v_mfma_f32_32x32x16_bf16 v[16:31], v[92:95], v[32:35], v[16:31]
	global_load_dwordx4 v[32:35], v[40:41], off
	s_nop 0
	global_load_dwordx4 v[36:39], v[36:37], off offset:16
	s_mov_b64 s[42:43], 0x4040
	v_add_co_u32_e32 v96, vcc, s33, v68
	s_waitcnt vmcnt(1)
	v_cvt_pk_bf16_f32 v32, v32, v33
	v_cvt_pk_bf16_f32 v33, v34, v35
	s_waitcnt vmcnt(0)
	v_cvt_pk_bf16_f32 v34, v36, v37
	v_cvt_pk_bf16_f32 v35, v38, v39
	v_lshl_add_u64 v[36:37], v[68:69], 0, s[42:43]
	s_mov_b64 s[42:43], 0x4080
	v_mfma_f32_32x32x16_bf16 v[48:63], v[80:83], v[32:35], 0
	global_load_dwordx4 v[32:35], v[40:41], off offset:64
	s_nop 0
	global_load_dwordx4 v[36:39], v[36:37], off offset:16
	v_addc_co_u32_e32 v97, vcc, 0, v69, vcc
	s_waitcnt vmcnt(1)
	v_cvt_pk_bf16_f32 v32, v32, v33
	v_cvt_pk_bf16_f32 v33, v34, v35
	s_waitcnt vmcnt(0)
	v_cvt_pk_bf16_f32 v34, v36, v37
	v_cvt_pk_bf16_f32 v35, v38, v39
	v_lshl_add_u64 v[36:37], v[68:69], 0, s[42:43]
	s_mov_b64 s[42:43], 0x40c0
	v_mfma_f32_32x32x16_bf16 v[48:63], v[84:87], v[32:35], v[48:63]
	global_load_dwordx4 v[32:35], v[40:41], off offset:128
	s_nop 0
	global_load_dwordx4 v[36:39], v[36:37], off offset:16
	s_waitcnt vmcnt(1)
	v_cvt_pk_bf16_f32 v32, v32, v33
	v_cvt_pk_bf16_f32 v33, v34, v35
	s_waitcnt vmcnt(0)
	v_cvt_pk_bf16_f32 v34, v36, v37
	v_cvt_pk_bf16_f32 v35, v38, v39
	v_lshl_add_u64 v[36:37], v[68:69], 0, s[42:43]
	s_mov_b64 s[42:43], 0x6000
	v_mfma_f32_32x32x16_bf16 v[48:63], v[88:91], v[32:35], v[48:63]
	global_load_dwordx4 v[32:35], v[40:41], off offset:192
	s_nop 0
	global_load_dwordx4 v[36:39], v[36:37], off offset:16
	s_waitcnt vmcnt(1)
	v_cvt_pk_bf16_f32 v32, v32, v33
	v_cvt_pk_bf16_f32 v33, v34, v35
	s_waitcnt vmcnt(0)
	v_cvt_pk_bf16_f32 v34, v36, v37
	v_cvt_pk_bf16_f32 v35, v38, v39
	v_lshl_add_u64 v[36:37], v[68:69], 0, s[42:43]
	s_mov_b64 s[42:43], 0x6040
	v_mfma_f32_32x32x16_bf16 v[48:63], v[92:95], v[32:35], v[48:63]
	global_load_dwordx4 v[32:35], v[96:97], off
	s_nop 0
	global_load_dwordx4 v[36:39], v[36:37], off offset:16
	v_lshl_add_u64 v[76:77], v[68:69], 0, s[42:43]
	global_load_dwordx4 v[72:75], v[96:97], off offset:64
	s_nop 0
	global_load_dwordx4 v[76:79], v[76:77], off offset:16
	s_mov_b64 s[42:43], 0x6080
	s_waitcnt vmcnt(3)
	v_cvt_pk_bf16_f32 v32, v32, v33
	v_cvt_pk_bf16_f32 v33, v34, v35
	s_waitcnt vmcnt(2)
	v_cvt_pk_bf16_f32 v34, v36, v37
	v_cvt_pk_bf16_f32 v35, v38, v39
	s_waitcnt vmcnt(1)
	v_cvt_pk_bf16_f32 v72, v72, v73
	v_cvt_pk_bf16_f32 v73, v74, v75
	v_mfma_f32_32x32x16_bf16 v[32:47], v[80:83], v[32:35], 0
	s_waitcnt vmcnt(0)
	v_cvt_pk_bf16_f32 v74, v76, v77
	v_cvt_pk_bf16_f32 v75, v78, v79
	v_lshl_add_u64 v[76:77], v[68:69], 0, s[42:43]
	s_mov_b64 s[42:43], 0x60c0
	v_lshl_add_u64 v[68:69], v[68:69], 0, s[42:43]
	v_mfma_f32_32x32x16_bf16 v[32:47], v[84:87], v[72:75], v[32:47]
	global_load_dwordx4 v[72:75], v[96:97], off offset:128
	s_nop 0
	global_load_dwordx4 v[76:79], v[76:77], off offset:16
	s_waitcnt vmcnt(1)
	v_cvt_pk_bf16_f32 v72, v72, v73
	v_cvt_pk_bf16_f32 v73, v74, v75
	s_waitcnt vmcnt(0)
	v_cvt_pk_bf16_f32 v74, v76, v77
	v_cvt_pk_bf16_f32 v75, v78, v79
	s_nop 1
	v_mfma_f32_32x32x16_bf16 v[32:47], v[88:91], v[72:75], v[32:47]
	global_load_dwordx4 v[72:75], v[96:97], off offset:192
	global_load_dwordx4 v[76:79], v[68:69], off offset:16
	s_waitcnt vmcnt(1)
	v_cvt_pk_bf16_f32 v72, v72, v73
	v_cvt_pk_bf16_f32 v73, v74, v75
	s_waitcnt vmcnt(0)
	v_cvt_pk_bf16_f32 v74, v76, v77
	v_cvt_pk_bf16_f32 v75, v78, v79
	s_nop 1
	v_mfma_f32_32x32x16_bf16 v[32:47], v[92:95], v[72:75], v[32:47]
	s_branch .LBB0_878
